# attention loop tails: dead exit tests removed (3 fewer scalar ops per iteration)
# speedup vs baseline: 1.0226x; 1.0011x over previous
.LBB0_374:
	s_lshl_b32 s2, s14, 15
	v_add_u32_e32 v170, s2, v135
	v_add_u32_e32 v178, s2, v136
	v_add_u32_e32 v186, s2, v137
	v_add_u32_e32 v194, s2, v138
	ds_read_b128 v[84:87], v170
	ds_read_b128 v[88:91], v170 offset:1024
	ds_read_b128 v[92:95], v178
	ds_read_b128 v[96:99], v178 offset:1024
	ds_read_b128 v[118:121], v186
	ds_read_b128 v[122:125], v186 offset:1024
	ds_read_b128 v[158:161], v194
	ds_read_b128 v[162:165], v194 offset:1024
	ds_read_b128 v[166:169], v170 offset:2048
	ds_read_b128 v[170:173], v170 offset:3072
	ds_read_b128 v[174:177], v178 offset:2048
	ds_read_b128 v[178:181], v178 offset:3072
	ds_read_b128 v[182:185], v186 offset:2048
	ds_read_b128 v[186:189], v186 offset:3072
	ds_read_b128 v[190:193], v194 offset:2048
	ds_read_b128 v[194:197], v194 offset:3072
	s_waitcnt lgkmcnt(0)
	v_mfma_f32_16x16x32_bf16 v[84:87], v[84:87], v[0:3], v[52:55]
	v_mfma_f32_16x16x32_bf16 v[118:121], v[118:121], v[8:11], v[52:55]
	v_mfma_f32_16x16x32_bf16 v[88:91], v[88:91], v[0:3], v[52:55]
	v_mfma_f32_16x16x32_bf16 v[122:125], v[122:125], v[8:11], v[52:55]
	v_mfma_f32_16x16x32_bf16 v[166:169], v[166:169], v[0:3], v[52:55]
	v_mfma_f32_16x16x32_bf16 v[182:185], v[182:185], v[8:11], v[52:55]
	v_mfma_f32_16x16x32_bf16 v[170:173], v[170:173], v[0:3], v[52:55]
	v_mfma_f32_16x16x32_bf16 v[186:189], v[186:189], v[8:11], v[52:55]
	v_mfma_f32_16x16x32_bf16 v[84:87], v[92:95], v[4:7], v[84:87]
	v_mfma_f32_16x16x32_bf16 v[92:95], v[158:161], v[12:15], v[118:121]
	v_mfma_f32_16x16x32_bf16 v[88:91], v[96:99], v[4:7], v[88:91]
	v_mfma_f32_16x16x32_bf16 v[96:99], v[162:165], v[12:15], v[122:125]
	v_mfma_f32_16x16x32_bf16 v[118:121], v[174:177], v[4:7], v[166:169]
	v_mfma_f32_16x16x32_bf16 v[122:125], v[190:193], v[12:15], v[182:185]
	v_mfma_f32_16x16x32_bf16 v[158:161], v[178:181], v[4:7], v[170:173]
	v_mfma_f32_16x16x32_bf16 v[162:165], v[194:197], v[12:15], v[186:189]
	v_add_f32_e32 v170, 0x42100000, v117
	v_fma_f32 v84, -v157, |v170|, v84
	v_add_f32_e32 v168, -1.0, v170
	v_fma_f32 v92, -v157, |v170|, v92
	v_exp_f32_e32 v166, v84
	v_fma_f32 v84, -v157, |v168|, v85
	v_exp_f32_e32 v167, v92
	v_exp_f32_e32 v92, v84
	v_fma_f32 v84, -v157, |v168|, v93
	v_exp_f32_e32 v93, v84
	v_add_f32_e32 v84, -2.0, v170
	v_fma_f32 v85, -v157, |v84|, v86
	v_fma_f32 v84, -v157, |v84|, v94
	v_exp_f32_e32 v169, v84
	v_add_f32_e32 v84, 0xc0400000, v170
	v_exp_f32_e32 v168, v85
	v_fma_f32 v85, -v157, |v84|, v87
	v_fma_f32 v84, -v157, |v84|, v95
	v_exp_f32_e32 v95, v84
	v_add_f32_e32 v84, 0x42000000, v117
	v_exp_f32_e32 v94, v85
	v_fma_f32 v85, -v157, |v84|, v88
	v_exp_f32_e32 v170, v85
	v_fma_f32 v85, -v157, |v84|, v96
	v_exp_f32_e32 v171, v85
	v_add_f32_e32 v85, -1.0, v84
	v_fma_f32 v86, -v157, |v85|, v89
	v_fma_f32 v85, -v157, |v85|, v97
	v_exp_f32_e32 v97, v85
	v_add_f32_e32 v85, -2.0, v84
	v_exp_f32_e32 v96, v86
	v_fma_f32 v86, -v157, |v85|, v90
	v_fma_f32 v85, -v157, |v85|, v98
	v_add_f32_e32 v84, 0xc0400000, v84
	v_exp_f32_e32 v173, v85
	v_fma_f32 v85, -v157, |v84|, v91
	v_fma_f32 v84, -v157, |v84|, v99
	v_exp_f32_e32 v90, v85
	v_exp_f32_e32 v91, v84
	v_add_f32_e32 v84, v114, v166
	v_add_f32_e32 v85, v115, v167
	v_exp_f32_e32 v172, v86
	v_add_f32_e32 v84, v84, v92
	v_add_f32_e32 v85, v85, v93
	v_add_f32_e32 v84, v84, v168
	v_add_f32_e32 v85, v85, v169
	v_cvt_pk_bf16_f32 v88, v167, v93
	v_cvt_pk_bf16_f32 v86, v170, v96
	v_cvt_pk_bf16_f32 v87, v172, v90
	v_add_f32_e32 v84, v84, v94
	v_add_f32_e32 v85, v85, v95
	v_add_f32_e32 v84, v84, v170
	v_add_f32_e32 v85, v85, v171
	v_add_f32_e32 v84, v84, v96
	v_add_f32_e32 v85, v85, v97
	v_add_f32_e32 v84, v84, v172
	v_add_f32_e32 v85, v85, v173
	v_add_f32_e32 v98, v84, v90
	v_add_f32_e32 v99, v85, v91
	v_cvt_pk_bf16_f32 v84, v166, v92
	v_cvt_pk_bf16_f32 v90, v171, v97
	v_cvt_pk_bf16_f32 v85, v168, v94
	v_cvt_pk_bf16_f32 v89, v169, v95
	v_add_f32_e32 v92, 4.0, v117
	v_fma_f32 v93, -v157, |v92|, v118
	v_exp_f32_e32 v96, v93
	v_fma_f32 v93, -v157, |v92|, v122
	v_exp_f32_e32 v97, v93
	v_add_f32_e32 v93, -1.0, v92
	v_fma_f32 v94, -v157, |v93|, v119
	v_fma_f32 v93, -v157, |v93|, v123
	v_exp_f32_e32 v119, v93
	v_add_f32_e32 v93, -2.0, v92
	v_exp_f32_e32 v118, v94
	v_fma_f32 v94, -v157, |v93|, v120
	v_exp_f32_e32 v122, v94
	v_fma_f32 v93, -v157, |v93|, v124
	v_add_f32_e32 v92, 0xc0400000, v92
	v_exp_f32_e32 v123, v93
	v_fma_f32 v93, -v157, |v92|, v121
	v_fma_f32 v92, -v157, |v92|, v125
	v_exp_f32_e32 v121, v92
	v_fma_f32 v92, -v157, |v117|, v158
	v_exp_f32_e32 v124, v92
	v_fma_f32 v92, -v157, |v117|, v162
	v_exp_f32_e32 v125, v92
	v_add_f32_e32 v92, -1.0, v117
	v_exp_f32_e32 v120, v93
	v_fma_f32 v93, -v157, |v92|, v159
	v_fma_f32 v92, -v157, |v92|, v163
	v_exp_f32_e32 v159, v92
	v_add_f32_e32 v92, -2.0, v117
	v_exp_f32_e32 v158, v93
	v_fma_f32 v93, -v157, |v92|, v160
	v_fma_f32 v92, -v157, |v92|, v164
	v_exp_f32_e32 v162, v93
	v_exp_f32_e32 v163, v92
	v_add_f32_e32 v92, v98, v96
	v_add_f32_e32 v93, v99, v97
	v_add_f32_e32 v94, 0xc0400000, v117
	v_add_f32_e32 v92, v92, v118
	v_add_f32_e32 v93, v93, v119
	v_fma_f32 v95, -v157, |v94|, v161
	v_add_f32_e32 v92, v92, v122
	v_add_f32_e32 v93, v93, v123
	v_fma_f32 v94, -v157, |v94|, v165
	v_add_f32_e32 v92, v92, v120
	v_add_f32_e32 v93, v93, v121
	v_exp_f32_e32 v98, v95
	v_exp_f32_e32 v99, v94
	v_add_f32_e32 v92, v92, v124
	v_add_f32_e32 v93, v93, v125
	v_cvt_pk_bf16_f32 v91, v173, v91
	v_cvt_pk_bf16_f32 v94, v124, v158
	v_cvt_pk_bf16_f32 v95, v162, v98
	v_add_f32_e32 v92, v92, v158
	v_add_f32_e32 v93, v93, v159
	v_add_f32_e32 v92, v92, v162
	v_add_f32_e32 v93, v93, v163
	v_add_f32_e32 v114, v92, v98
	v_add_f32_e32 v115, v93, v99
	v_cvt_pk_bf16_f32 v92, v96, v118
	v_cvt_pk_bf16_f32 v93, v122, v120
	v_cvt_pk_bf16_f32 v96, v97, v119
	v_cvt_pk_bf16_f32 v97, v123, v121
	v_cvt_pk_bf16_f32 v98, v125, v159
	v_cvt_pk_bf16_f32 v99, v163, v99
	s_and_b64 vcc, exec, s[54:55]
	s_cbranch_vccnz .LBB0_371
.LBB0_375:
	s_lshl_b32 s2, s14, 15
	v_add_u32_e32 v178, s2, v139
	v_add_u32_e32 v210, s2, v154
	ds_read_b128 v[118:121], v178 offset:16384
	ds_read_b128 v[122:125], v178 offset:16896
	ds_read_b128 v[158:161], v178 offset:17408
	ds_read_b128 v[162:165], v178 offset:17920
	ds_read_b128 v[166:169], v178 offset:18432
	ds_read_b128 v[170:173], v178 offset:18944
	ds_read_b128 v[174:177], v178 offset:19456
	ds_read_b128 v[178:181], v178 offset:19968
	ds_read_b128 v[182:185], v210 offset:16384
	ds_read_b128 v[186:189], v210 offset:16896
	ds_read_b128 v[190:193], v210 offset:17408
	ds_read_b128 v[194:197], v210 offset:17920
	ds_read_b128 v[198:201], v210 offset:18432
	ds_read_b128 v[202:205], v210 offset:18944
	ds_read_b128 v[206:209], v210 offset:19456
	ds_read_b128 v[228:231], v210 offset:19968
	s_waitcnt lgkmcnt(0)
	v_mfma_f32_16x16x32_bf16 v[56:59], v[118:121], v[84:87], v[56:59]
	v_mfma_f32_16x16x32_bf16 v[48:51], v[118:121], v[88:91], v[48:51]
	v_mfma_f32_16x16x32_bf16 v[60:63], v[122:125], v[84:87], v[60:63]
	v_mfma_f32_16x16x32_bf16 v[44:47], v[122:125], v[88:91], v[44:47]
	v_mfma_f32_16x16x32_bf16 v[64:67], v[158:161], v[84:87], v[64:67]
	v_mfma_f32_16x16x32_bf16 v[40:43], v[158:161], v[88:91], v[40:43]
	v_mfma_f32_16x16x32_bf16 v[68:71], v[162:165], v[84:87], v[68:71]
	v_mfma_f32_16x16x32_bf16 v[36:39], v[162:165], v[88:91], v[36:39]
	v_mfma_f32_16x16x32_bf16 v[72:75], v[166:169], v[84:87], v[72:75]
	v_mfma_f32_16x16x32_bf16 v[32:35], v[166:169], v[88:91], v[32:35]
	v_mfma_f32_16x16x32_bf16 v[76:79], v[170:173], v[84:87], v[76:79]
	v_mfma_f32_16x16x32_bf16 v[24:27], v[170:173], v[88:91], v[24:27]
	v_mfma_f32_16x16x32_bf16 v[80:83], v[174:177], v[84:87], v[80:83]
	v_mfma_f32_16x16x32_bf16 v[20:23], v[174:177], v[88:91], v[20:23]
	v_mfma_f32_16x16x32_bf16 v[28:31], v[178:181], v[84:87], v[28:31]
	v_mfma_f32_16x16x32_bf16 v[16:19], v[178:181], v[88:91], v[16:19]
	v_mfma_f32_16x16x32_bf16 v[56:59], v[182:185], v[92:95], v[56:59]
	v_mfma_f32_16x16x32_bf16 v[48:51], v[182:185], v[96:99], v[48:51]
	v_mfma_f32_16x16x32_bf16 v[60:63], v[186:189], v[92:95], v[60:63]
	v_mfma_f32_16x16x32_bf16 v[44:47], v[186:189], v[96:99], v[44:47]
	v_mfma_f32_16x16x32_bf16 v[64:67], v[190:193], v[92:95], v[64:67]
	v_mfma_f32_16x16x32_bf16 v[40:43], v[190:193], v[96:99], v[40:43]
	v_mfma_f32_16x16x32_bf16 v[68:71], v[194:197], v[92:95], v[68:71]
	v_mfma_f32_16x16x32_bf16 v[36:39], v[194:197], v[96:99], v[36:39]
	v_mfma_f32_16x16x32_bf16 v[72:75], v[198:201], v[92:95], v[72:75]
	v_mfma_f32_16x16x32_bf16 v[32:35], v[198:201], v[96:99], v[32:35]
	v_mfma_f32_16x16x32_bf16 v[76:79], v[202:205], v[92:95], v[76:79]
	v_mfma_f32_16x16x32_bf16 v[24:27], v[202:205], v[96:99], v[24:27]
	v_mfma_f32_16x16x32_bf16 v[80:83], v[206:209], v[92:95], v[80:83]
	v_mfma_f32_16x16x32_bf16 v[20:23], v[206:209], v[96:99], v[20:23]
	v_mfma_f32_16x16x32_bf16 v[28:31], v[228:231], v[92:95], v[28:31]
	v_mfma_f32_16x16x32_bf16 v[16:19], v[228:231], v[96:99], v[16:19]
	v_add_f32_e32 v117, 0xc2800000, v117
.LBB0_376:
	s_mov_b32 s1, s15
	s_mov_b32 s0, s14
	s_branch .LBB0_367
